# v44 + hgrn chain steps wait only for the next chunk LDS-DMA (vmcnt(16)) instead of draining the 16 output stores before the step barrier
# baseline (speedup 1.0000x reference)
.LBB0_489:
	s_bitcmp1_b32 s73, 0
	s_cselect_b32 s54, 0x10800, 0
	s_add_i32 s54, s62, s54
	v_add3_u32 v186, s54, v149, v161
	v_add_u32_e32 v185, s54, v160
	v_add_u32_e32 v20, v186, v118
	ds_read_b128 v[68:71], v185 offset:32768
	ds_read_b128 v[72:75], v185 offset:32784
	ds_read_b128 v[76:79], v185 offset:32800
	ds_read_b128 v[80:83], v185 offset:32816
	ds_read2st64_b64 v[84:87], v20 offset1:16
	v_add_u32_e32 v20, v186, v169
	ds_read2st64_b64 v[88:91], v20 offset1:16
	v_add_u32_e32 v20, v186, v170
	ds_read2st64_b64 v[92:95], v20 offset1:16
	v_add_u32_e32 v20, v186, v171
	ds_read2st64_b64 v[20:23], v20 offset1:16
	s_waitcnt lgkmcnt(0)
	v_pk_mul_f32 v[4:5], v[4:5], v[68:69]
	v_pk_mul_f32 v[6:7], v[6:7], v[70:71]
	v_mov_b32_e32 v68, v84
	v_mov_b32_e32 v69, v85
	v_mov_b32_e32 v70, v88
	v_mov_b32_e32 v71, v89
	v_mov_b32_e32 v88, v86
	v_mov_b32_e32 v89, v87
	v_pk_mul_f32 v[8:9], v[8:9], v[72:73]
	v_pk_mul_f32 v[10:11], v[10:11], v[74:75]
	v_cvt_pk_bf16_f32 v72, v4, v5
	v_cvt_pk_bf16_f32 v73, v6, v7
	v_cvt_pk_bf16_f32 v74, v8, v9
	v_cvt_pk_bf16_f32 v75, v10, v11
	v_pk_mul_f32 v[12:13], v[12:13], v[76:77]
	v_pk_mul_f32 v[16:17], v[16:17], v[80:81]
	v_pk_mul_f32 v[14:15], v[14:15], v[78:79]
	v_pk_mul_f32 v[18:19], v[18:19], v[82:83]
	v_mov_b32_e32 v188, v92
	v_mov_b32_e32 v189, v93
	v_mov_b32_e32 v190, v20
	v_mov_b32_e32 v191, v21
	v_mov_b32_e32 v20, v94
	v_mov_b32_e32 v21, v95
	v_mfma_f32_32x32x16_bf16 v[84:99], v[88:91], v[68:71], 0
	v_cvt_pk_bf16_f32 v192, v12, v13
	v_cvt_pk_bf16_f32 v193, v14, v15
	v_cvt_pk_bf16_f32 v194, v16, v17
	v_cvt_pk_bf16_f32 v195, v18, v19
	v_mfma_f32_32x32x16_bf16 v[68:83], v[68:71], v[72:75], 0
	v_mfma_f32_32x32x16_bf16 v[84:99], v[20:23], v[188:191], v[84:99]
	v_mfma_f32_32x32x16_bf16 v[68:83], v[188:191], v[192:195], v[68:83]
	v_add_u32_e32 v187, v186, v172
	ds_read_b128 v[20:23], v185 offset:32896
	ds_read_b128 v[188:191], v185 offset:32912
	ds_read_b128 v[192:195], v185 offset:32928
	ds_read2st64_b64 v[200:203], v187 offset1:16
	v_add_u32_e32 v187, v186, v173
	ds_read2st64_b64 v[204:207], v187 offset1:16
	v_add_u32_e32 v187, v186, v174
	ds_read2st64_b64 v[208:211], v187 offset1:16
	s_waitcnt lgkmcnt(0)
	v_mov_b32_e32 v216, v200
	v_mov_b32_e32 v217, v201
	v_mov_b32_e32 v218, v204
	v_mov_b32_e32 v219, v205
	v_mov_b32_e32 v204, v202
	v_mov_b32_e32 v205, v203
	v_add_u32_e32 v187, v186, v175
	ds_read2st64_b64 v[212:215], v187 offset1:16
	v_pk_mul_f32 v[36:37], v[36:37], v[20:21]
	v_pk_mul_f32 v[40:41], v[40:41], v[188:189]
	v_pk_mul_f32 v[38:39], v[38:39], v[22:23]
	v_pk_mul_f32 v[42:43], v[42:43], v[190:191]
	v_cvt_pk_bf16_f32 v188, v36, v37
	v_cvt_pk_bf16_f32 v189, v38, v39
	v_cvt_pk_bf16_f32 v190, v40, v41
	v_cvt_pk_bf16_f32 v191, v42, v43
	v_mfma_f32_32x32x16_bf16 v[84:99], v[204:207], v[216:219], v[84:99]
	s_waitcnt lgkmcnt(0)
	v_mov_b32_e32 v22, v212
	v_mov_b32_e32 v23, v213
	v_mov_b32_e32 v212, v210
	v_mov_b32_e32 v213, v211
	v_mov_b32_e32 v20, v208
	v_mov_b32_e32 v21, v209
	v_pk_mul_f32 v[44:45], v[44:45], v[192:193]
	v_mfma_f32_32x32x16_bf16 v[68:83], v[216:219], v[188:191], v[68:83]
	ds_read_b128 v[188:191], v185 offset:32944
	v_mul_f32_e64 v46, v46, v194
	v_mul_f32_e64 v47, v47, v195
	s_waitcnt lgkmcnt(0)
	v_mul_f32_e64 v48, v48, v188
	v_mul_f32_e64 v49, v49, v189
	v_pk_mul_f32 v[50:51], v[50:51], v[190:191]
	v_cvt_pk_bf16_f32 v188, v44, v45
	v_cvt_pk_bf16_f32 v189, v46, v47
	v_cvt_pk_bf16_f32 v190, v48, v49
	v_cvt_pk_bf16_f32 v191, v50, v51
	v_mfma_f32_32x32x16_bf16 v[84:99], v[212:215], v[20:23], v[84:99]
	s_nop 0
	v_mfma_f32_32x32x16_bf16 v[68:83], v[20:23], v[188:191], v[68:83]
	v_add_u32_e32 v187, v186, v176
	ds_read_b128 v[20:23], v185 offset:33024
	ds_read_b128 v[188:191], v185 offset:33040
	ds_read_b128 v[192:195], v185 offset:33056
	ds_read2st64_b64 v[200:203], v187 offset1:16
	v_add_u32_e32 v187, v186, v177
	ds_read2st64_b64 v[204:207], v187 offset1:16
	v_add_u32_e32 v187, v186, v178
	ds_read2st64_b64 v[208:211], v187 offset1:16
	s_waitcnt lgkmcnt(0)
	v_mov_b32_e32 v216, v200
	v_mov_b32_e32 v217, v201
	v_mov_b32_e32 v218, v204
	v_mov_b32_e32 v219, v205
	v_mov_b32_e32 v204, v202
	v_mov_b32_e32 v205, v203
	v_add_u32_e32 v187, v186, v179
	ds_read2st64_b64 v[212:215], v187 offset1:16
	v_pk_mul_f32 v[52:53], v[52:53], v[20:21]
	v_pk_mul_f32 v[56:57], v[56:57], v[188:189]
	v_pk_mul_f32 v[54:55], v[54:55], v[22:23]
	v_pk_mul_f32 v[58:59], v[58:59], v[190:191]
	v_cvt_pk_bf16_f32 v188, v52, v53
	v_cvt_pk_bf16_f32 v189, v54, v55
	v_cvt_pk_bf16_f32 v190, v56, v57
	v_cvt_pk_bf16_f32 v191, v58, v59
	v_mfma_f32_32x32x16_bf16 v[84:99], v[204:207], v[216:219], v[84:99]
	s_waitcnt lgkmcnt(0)
	v_mov_b32_e32 v22, v212
	v_mov_b32_e32 v23, v213
	v_mov_b32_e32 v212, v210
	v_mov_b32_e32 v213, v211
	v_mov_b32_e32 v20, v208
	v_mov_b32_e32 v21, v209
	v_pk_mul_f32 v[60:61], v[60:61], v[192:193]
	v_mfma_f32_32x32x16_bf16 v[68:83], v[216:219], v[188:191], v[68:83]
	ds_read_b128 v[188:191], v185 offset:33072
	v_mul_f32_e64 v62, v62, v194
	v_mul_f32_e64 v63, v63, v195
	s_waitcnt lgkmcnt(0)
	v_mul_f32_e64 v64, v64, v188
	v_mul_f32_e64 v65, v65, v189
	v_pk_mul_f32 v[66:67], v[66:67], v[190:191]
	v_cvt_pk_bf16_f32 v188, v60, v61
	v_cvt_pk_bf16_f32 v189, v62, v63
	v_cvt_pk_bf16_f32 v190, v64, v65
	v_cvt_pk_bf16_f32 v191, v66, v67
	v_mfma_f32_32x32x16_bf16 v[84:99], v[212:215], v[20:23], v[84:99]
	s_nop 0
	v_mfma_f32_32x32x16_bf16 v[68:83], v[20:23], v[188:191], v[68:83]
	v_add_u32_e32 v187, v186, v180
	ds_read_b128 v[20:23], v185 offset:33152
	ds_read_b128 v[188:191], v185 offset:33168
	ds_read_b128 v[192:195], v185 offset:33184
	ds_read_b128 v[200:203], v185 offset:33200
	ds_read2st64_b64 v[204:207], v187 offset1:16
	v_add_u32_e32 v187, v186, v181
	ds_read2st64_b64 v[208:211], v187 offset1:16
	s_waitcnt lgkmcnt(0)
	v_pk_mul_f32 v[20:21], v[24:25], v[20:21]
	v_pk_mul_f32 v[24:25], v[158:159], v[188:189]
	v_add_u32_e32 v187, v186, v182
	v_add_u32_e32 v186, v186, v183
	v_mov_b32_e32 v158, v208
	v_mov_b32_e32 v159, v209
	v_mov_b32_e32 v208, v206
	v_mov_b32_e32 v209, v207
	ds_read2st64_b64 v[212:215], v187 offset1:16
	ds_read2st64_b64 v[216:219], v186 offset1:16
	v_pk_mul_f32 v[22:23], v[156:157], v[22:23]
	v_mov_b32_e32 v156, v204
	v_mov_b32_e32 v157, v205
	v_pk_mul_f32 v[28:29], v[28:29], v[192:193]
	s_waitcnt lgkmcnt(0)
	v_mov_b32_e32 v188, v216
	v_mfma_f32_32x32x16_bf16 v[84:99], v[208:211], v[156:159], v[84:99]
	v_mov_b32_e32 v189, v217
	v_mov_b32_e32 v216, v214
	v_mov_b32_e32 v217, v215
	v_mul_f32_e64 v32, v32, v200
	v_mul_f32_e64 v33, v33, v201
	v_pk_mul_f32 v[26:27], v[26:27], v[190:191]
	v_pk_mul_f32 v[30:31], v[30:31], v[194:195]
	v_pk_mul_f32 v[34:35], v[34:35], v[202:203]
	v_mov_b32_e32 v186, v212
	v_mov_b32_e32 v187, v213
	v_cvt_pk_bf16_f32 v190, v20, v21
	v_cvt_pk_bf16_f32 v191, v22, v23
	v_cvt_pk_bf16_f32 v192, v24, v25
	v_cvt_pk_bf16_f32 v193, v26, v27
	v_cvt_pk_bf16_f32 v194, v28, v29
	v_cvt_pk_bf16_f32 v195, v30, v31
	v_cvt_pk_bf16_f32 v196, v32, v33
	v_cvt_pk_bf16_f32 v197, v34, v35
	v_mfma_f32_32x32x16_bf16 v[84:99], v[216:219], v[186:189], v[84:99]
	v_mfma_f32_32x32x16_bf16 v[68:83], v[156:159], v[190:193], v[68:83]
	v_add_u32_e32 v159, s54, v162
	s_nop 9
	v_cndmask_b32_e64 v200, 0, v84, s[12:13]
	v_cndmask_b32_e64 v201, 0, v85, s[14:15]
	v_cndmask_b32_e64 v202, 0, v86, s[16:17]
	v_cndmask_b32_e64 v203, 0, v87, s[18:19]
	v_cndmask_b32_e64 v204, 0, v88, s[20:21]
	v_cndmask_b32_e64 v205, 0, v89, s[22:23]
	v_mfma_f32_32x32x16_bf16 v[68:83], v[186:189], v[194:197], v[68:83]
	v_cndmask_b32_e64 v206, 0, v90, s[24:25]
	v_cndmask_b32_e64 v91, 0, v91, s[26:27]
	v_add3_u32 v84, v159, v163, v161
	v_add3_u32 v86, v159, v164, v161
	ds_read_b64 v[84:85], v84 offset:24576
	ds_read_b64 v[86:87], v86 offset:24576
	v_cvt_pk_bf16_f32 v88, v200, v201
	v_cvt_pk_bf16_f32 v89, v202, v203
	v_cvt_pk_bf16_f32 v90, v204, v205
	v_cvt_pk_bf16_f32 v91, v206, v91
	v_cndmask_b32_e64 v207, 0, v92, s[28:29]
	v_cndmask_b32_e64 v156, 0, v93, s[30:31]
	s_waitcnt lgkmcnt(0)
	v_mfma_f32_32x32x16_bf16 v[68:83], v[88:91], v[84:87], v[68:83]
	v_cndmask_b32_e64 v157, 0, v94, s[34:35]
	v_cndmask_b32_e64 v158, 0, v95, s[36:37]
	v_cndmask_b32_e64 v96, 0, v96, s[38:39]
	v_cndmask_b32_e64 v97, 0, v97, s[40:41]
	v_cndmask_b32_e64 v98, 0, v98, s[42:43]
	v_cndmask_b32_e64 v99, 0, v99, s[44:45]
	v_add3_u32 v92, v159, v165, v161
	v_add3_u32 v94, v159, v166, v161
	ds_read_b64 v[92:93], v92 offset:24576
	ds_read_b64 v[94:95], v94 offset:24576
	v_cvt_pk_bf16_f32 v84, v207, v156
	v_cvt_pk_bf16_f32 v85, v157, v158
	v_cvt_pk_bf16_f32 v86, v96, v97
	v_cvt_pk_bf16_f32 v87, v98, v99
	s_lshl_b32 s55, s72, 5
	s_add_i32 s55, s55, s60
	s_waitcnt lgkmcnt(0)
	v_mfma_f32_32x32x16_bf16 v[68:83], v[84:87], v[92:95], v[68:83]
	v_mad_u64_u32 v[84:85], s[72:73], s55, v199, v[122:123]
	v_lshl_add_u64 v[86:87], v[84:85], 0, v[2:3]
	s_mov_b32 s55, 0x8000
	s_nop 8
	v_cvt_pk_bf16_f32 v68, v68, s0
	global_store_short v[86:87], v68, off
	v_cvt_pk_bf16_f32 v86, v69, s0
	v_lshl_add_u64 v[68:69], v[84:85], 0, v[126:127]
	global_store_short v[68:69], v86, off
	v_add_co_u32_e32 v68, vcc, s55, v68
	v_cvt_pk_bf16_f32 v70, v70, s0
	s_nop 0
	v_addc_co_u32_e32 v69, vcc, 0, v69, vcc
	global_store_short v[68:69], v70, off offset:512
	v_cvt_pk_bf16_f32 v70, v71, s0
	v_lshl_add_u64 v[68:69], v[84:85], 0, v[128:129]
	global_store_short v[68:69], v70, off
	v_cvt_pk_bf16_f32 v70, v72, s0
	v_lshl_add_u64 v[68:69], v[84:85], 0, v[130:131]
	global_store_short v[68:69], v70, off
	v_cvt_pk_bf16_f32 v70, v73, s0
	v_lshl_add_u64 v[68:69], v[84:85], 0, v[132:133]
	global_store_short v[68:69], v70, off
	v_cvt_pk_bf16_f32 v70, v74, s0
	v_lshl_add_u64 v[68:69], v[84:85], 0, v[134:135]
	global_store_short v[68:69], v70, off
	v_cvt_pk_bf16_f32 v70, v75, s0
	v_lshl_add_u64 v[68:69], v[84:85], 0, v[136:137]
	global_store_short v[68:69], v70, off
	v_cvt_pk_bf16_f32 v70, v76, s0
	v_lshl_add_u64 v[68:69], v[84:85], 0, v[138:139]
	global_store_short v[68:69], v70, off
	v_cvt_pk_bf16_f32 v70, v77, s0
	v_lshl_add_u64 v[68:69], v[84:85], 0, v[140:141]
	global_store_short v[68:69], v70, off
	v_cvt_pk_bf16_f32 v70, v78, s0
	v_lshl_add_u64 v[68:69], v[84:85], 0, v[142:143]
	global_store_short v[68:69], v70, off
	v_cvt_pk_bf16_f32 v70, v79, s0
	v_lshl_add_u64 v[68:69], v[84:85], 0, v[144:145]
	global_store_short v[68:69], v70, off
	v_cvt_pk_bf16_f32 v70, v80, s0
	v_lshl_add_u64 v[68:69], v[84:85], 0, v[146:147]
	global_store_short v[68:69], v70, off
	v_cvt_pk_bf16_f32 v70, v81, s0
	v_lshl_add_u64 v[68:69], v[84:85], 0, v[150:151]
	global_store_short v[68:69], v70, off
	v_cvt_pk_bf16_f32 v70, v82, s0
	v_lshl_add_u64 v[68:69], v[84:85], 0, v[152:153]
	global_store_short v[68:69], v70, off
	v_cvt_pk_bf16_f32 v70, v83, s0
	v_lshl_add_u64 v[68:69], v[84:85], 0, v[154:155]
	global_store_short v[68:69], v70, off
	v_add_u32_e32 v80, s54, v184
	v_add_u32_e32 v92, v80, v167
	ds_read_b128 v[76:79], v92 offset:16384
	v_add_u32_e32 v68, v159, v167
	ds_read_b128 v[68:71], v68 offset:24576
	v_add_u32_e32 v93, v80, v168
	v_add_u32_e32 v72, v159, v168
	ds_read_b128 v[80:83], v93 offset:16384
	ds_read_b128 v[72:75], v72 offset:24576
	s_add_i32 s70, s70, -1
	s_cmpk_eq_i32 s71, 0x80
	s_waitcnt lgkmcnt(0)
	v_mfma_f32_32x32x16_bf16 v[4:19], v[76:79], v[68:71], v[4:19]
	s_mov_b32 s73, s71
	v_mfma_f32_32x32x16_bf16 v[4:19], v[80:83], v[72:75], v[4:19]
	ds_read_b128 v[76:79], v185 offset:33280
	ds_read_b128 v[80:83], v185 offset:33296
	ds_read_b128 v[84:87], v185 offset:33312
	ds_read_b128 v[88:91], v185 offset:33328
	s_waitcnt lgkmcnt(0)
	s_nop 6
	v_pk_mul_f32 v[10:11], v[10:11], v[82:83]
	v_pk_mul_f32 v[8:9], v[8:9], v[80:81]
	v_pk_mul_f32 v[6:7], v[6:7], v[78:79]
	v_pk_mul_f32 v[4:5], v[4:5], v[76:77]
	ds_read_b128 v[76:79], v92 offset:18432
	ds_read_b128 v[80:83], v93 offset:18432
	s_waitcnt lgkmcnt(0)
	v_mfma_f32_32x32x16_bf16 v[36:51], v[76:79], v[68:71], v[36:51]
	v_mul_f32_e64 v18, v18, v90
	v_mul_f32_e64 v19, v19, v91
	v_mul_f32_e64 v16, v16, v88
	v_mul_f32_e64 v17, v17, v89
	v_mul_f32_e64 v14, v14, v86
	v_mul_f32_e64 v15, v15, v87
	v_pk_mul_f32 v[12:13], v[12:13], v[84:85]
	v_mfma_f32_32x32x16_bf16 v[36:51], v[80:83], v[72:75], v[36:51]
	ds_read_b128 v[76:79], v185 offset:33408
	ds_read_b128 v[80:83], v185 offset:33424
	ds_read_b128 v[84:87], v185 offset:33440
	ds_read_b128 v[88:91], v185 offset:33456
	s_waitcnt lgkmcnt(0)
	s_nop 6
	v_pk_mul_f32 v[42:43], v[42:43], v[82:83]
	v_pk_mul_f32 v[40:41], v[40:41], v[80:81]
	v_pk_mul_f32 v[38:39], v[38:39], v[78:79]
	v_pk_mul_f32 v[36:37], v[36:37], v[76:77]
	ds_read_b128 v[76:79], v92 offset:20480
	ds_read_b128 v[80:83], v93 offset:20480
	s_waitcnt lgkmcnt(0)
	v_mfma_f32_32x32x16_bf16 v[52:67], v[76:79], v[68:71], v[52:67]
	v_mul_f32_e64 v50, v50, v90
	v_mul_f32_e64 v51, v51, v91
	v_mul_f32_e64 v48, v48, v88
	v_mul_f32_e64 v49, v49, v89
	v_mul_f32_e64 v46, v46, v86
	v_mul_f32_e64 v47, v47, v87
	v_pk_mul_f32 v[44:45], v[44:45], v[84:85]
	v_mfma_f32_32x32x16_bf16 v[52:67], v[80:83], v[72:75], v[52:67]
	ds_read_b128 v[76:79], v185 offset:33536
	ds_read_b128 v[80:83], v185 offset:33552
	ds_read_b128 v[84:87], v185 offset:33568
	ds_read_b128 v[88:91], v185 offset:33584
	s_waitcnt lgkmcnt(0)
	s_nop 6
	v_pk_mul_f32 v[58:59], v[58:59], v[82:83]
	v_pk_mul_f32 v[56:57], v[56:57], v[80:81]
	v_pk_mul_f32 v[54:55], v[54:55], v[78:79]
	v_pk_mul_f32 v[52:53], v[52:53], v[76:77]
	ds_read_b128 v[76:79], v92 offset:22528
	ds_read_b128 v[80:83], v93 offset:22528
	s_waitcnt lgkmcnt(0)
	v_mfma_f32_32x32x16_bf16 v[20:35], v[76:79], v[68:71], v[20:35]
	v_mul_f32_e64 v66, v66, v90
	v_mul_f32_e64 v67, v67, v91
	v_mul_f32_e64 v64, v64, v88
	v_mul_f32_e64 v65, v65, v89
	v_mul_f32_e64 v62, v62, v86
	v_mul_f32_e64 v63, v63, v87
	v_pk_mul_f32 v[60:61], v[60:61], v[84:85]
	v_mfma_f32_32x32x16_bf16 v[20:35], v[80:83], v[72:75], v[20:35]
	ds_read_b128 v[68:71], v185 offset:33664
	ds_read_b128 v[72:75], v185 offset:33680
	ds_read_b128 v[76:79], v185 offset:33696
	ds_read_b128 v[80:83], v185 offset:33712
	s_cbranch_scc1 .Lhg_lat_last
	s_waitcnt vmcnt(16) lgkmcnt(0)
	s_branch .Lhg_lat_bar

.Lhg_lat_bar:
	s_barrier
	s_nop 5
	v_pk_mul_f32 v[34:35], v[34:35], v[82:83]
	v_pk_mul_f32 v[32:33], v[32:33], v[80:81]
	v_pk_mul_f32 v[30:31], v[30:31], v[78:79]
	v_pk_mul_f32 v[28:29], v[28:29], v[76:77]
	v_pk_mul_f32 v[26:27], v[26:27], v[74:75]
	v_pk_mul_f32 v[158:159], v[24:25], v[72:73]
	v_pk_mul_f32 v[156:157], v[22:23], v[70:71]
	v_pk_mul_f32 v[24:25], v[20:21], v[68:69]
	s_cbranch_scc1 .LBB0_493

.LBB0_643:
	s_bitcmp1_b32 s66, 0
	s_cselect_b32 s48, 0x10800, 0
	s_add_i32 s48, s55, s48
	v_add3_u32 v184, s48, v149, v159
	v_add_u32_e32 v183, s48, v158
	v_add_u32_e32 v20, v184, v100
	ds_read_b128 v[68:71], v183 offset:32768
	ds_read_b128 v[72:75], v183 offset:32784
	ds_read_b128 v[76:79], v183 offset:32800
	ds_read_b128 v[80:83], v183 offset:32816
	ds_read2st64_b64 v[84:87], v20 offset1:16
	v_add_u32_e32 v20, v184, v167
	ds_read2st64_b64 v[88:91], v20 offset1:16
	v_add_u32_e32 v20, v184, v168
	ds_read2st64_b64 v[92:95], v20 offset1:16
	v_add_u32_e32 v20, v184, v169
	ds_read2st64_b64 v[20:23], v20 offset1:16
	s_waitcnt lgkmcnt(0)
	v_pk_mul_f32 v[4:5], v[4:5], v[68:69]
	v_pk_mul_f32 v[6:7], v[6:7], v[70:71]
	v_mov_b32_e32 v68, v84
	v_mov_b32_e32 v69, v85
	v_mov_b32_e32 v70, v88
	v_mov_b32_e32 v71, v89
	v_mov_b32_e32 v88, v86
	v_mov_b32_e32 v89, v87
	v_pk_mul_f32 v[8:9], v[8:9], v[72:73]
	v_pk_mul_f32 v[10:11], v[10:11], v[74:75]
	v_cvt_pk_bf16_f32 v72, v4, v5
	v_cvt_pk_bf16_f32 v73, v6, v7
	v_cvt_pk_bf16_f32 v74, v8, v9
	v_cvt_pk_bf16_f32 v75, v10, v11
	v_pk_mul_f32 v[12:13], v[12:13], v[76:77]
	v_pk_mul_f32 v[16:17], v[16:17], v[80:81]
	v_pk_mul_f32 v[14:15], v[14:15], v[78:79]
	v_pk_mul_f32 v[18:19], v[18:19], v[82:83]
	v_mov_b32_e32 v186, v92
	v_mov_b32_e32 v187, v93
	v_mov_b32_e32 v188, v20
	v_mov_b32_e32 v189, v21
	v_mov_b32_e32 v20, v94
	v_mov_b32_e32 v21, v95
	v_mfma_f32_32x32x16_bf16 v[84:99], v[88:91], v[68:71], 0
	v_cvt_pk_bf16_f32 v190, v12, v13
	v_cvt_pk_bf16_f32 v191, v14, v15
	v_cvt_pk_bf16_f32 v192, v16, v17
	v_cvt_pk_bf16_f32 v193, v18, v19
	v_mfma_f32_32x32x16_bf16 v[68:83], v[68:71], v[72:75], 0
	v_mfma_f32_32x32x16_bf16 v[84:99], v[20:23], v[186:189], v[84:99]
	v_mfma_f32_32x32x16_bf16 v[68:83], v[186:189], v[190:193], v[68:83]
	v_add_u32_e32 v185, v184, v170
	ds_read_b128 v[20:23], v183 offset:32896
	ds_read_b128 v[186:189], v183 offset:32912
	ds_read_b128 v[190:193], v183 offset:32928
	ds_read2st64_b64 v[194:197], v185 offset1:16
	v_add_u32_e32 v185, v184, v171
	ds_read2st64_b64 v[200:203], v185 offset1:16
	v_add_u32_e32 v185, v184, v172
	ds_read2st64_b64 v[204:207], v185 offset1:16
	s_waitcnt lgkmcnt(0)
	v_mov_b32_e32 v212, v194
	v_mov_b32_e32 v213, v195
	v_mov_b32_e32 v214, v200
	v_mov_b32_e32 v215, v201
	v_mov_b32_e32 v200, v196
	v_mov_b32_e32 v201, v197
	v_add_u32_e32 v185, v184, v173
	ds_read2st64_b64 v[208:211], v185 offset1:16
	v_pk_mul_f32 v[36:37], v[36:37], v[20:21]
	v_pk_mul_f32 v[40:41], v[40:41], v[186:187]
	v_pk_mul_f32 v[38:39], v[38:39], v[22:23]
	v_pk_mul_f32 v[42:43], v[42:43], v[188:189]
	v_cvt_pk_bf16_f32 v186, v36, v37
	v_cvt_pk_bf16_f32 v187, v38, v39
	v_cvt_pk_bf16_f32 v188, v40, v41
	v_cvt_pk_bf16_f32 v189, v42, v43
	v_mfma_f32_32x32x16_bf16 v[84:99], v[200:203], v[212:215], v[84:99]
	s_waitcnt lgkmcnt(0)
	v_mov_b32_e32 v22, v208
	v_mov_b32_e32 v23, v209
	v_mov_b32_e32 v208, v206
	v_mov_b32_e32 v209, v207
	v_mov_b32_e32 v20, v204
	v_mov_b32_e32 v21, v205
	v_pk_mul_f32 v[44:45], v[44:45], v[190:191]
	v_mfma_f32_32x32x16_bf16 v[68:83], v[212:215], v[186:189], v[68:83]
	ds_read_b128 v[186:189], v183 offset:32944
	v_mul_f32_e64 v46, v46, v192
	v_mul_f32_e64 v47, v47, v193
	s_waitcnt lgkmcnt(0)
	v_mul_f32_e64 v48, v48, v186
	v_mul_f32_e64 v49, v49, v187
	v_pk_mul_f32 v[50:51], v[50:51], v[188:189]
	v_cvt_pk_bf16_f32 v186, v44, v45
	v_cvt_pk_bf16_f32 v187, v46, v47
	v_cvt_pk_bf16_f32 v188, v48, v49
	v_cvt_pk_bf16_f32 v189, v50, v51
	v_mfma_f32_32x32x16_bf16 v[84:99], v[208:211], v[20:23], v[84:99]
	s_nop 0
	v_mfma_f32_32x32x16_bf16 v[68:83], v[20:23], v[186:189], v[68:83]
	v_add_u32_e32 v185, v184, v174
	ds_read_b128 v[20:23], v183 offset:33024
	ds_read_b128 v[186:189], v183 offset:33040
	ds_read_b128 v[190:193], v183 offset:33056
	ds_read2st64_b64 v[194:197], v185 offset1:16
	v_add_u32_e32 v185, v184, v175
	ds_read2st64_b64 v[200:203], v185 offset1:16
	v_add_u32_e32 v185, v184, v176
	ds_read2st64_b64 v[204:207], v185 offset1:16
	s_waitcnt lgkmcnt(0)
	v_mov_b32_e32 v212, v194
	v_mov_b32_e32 v213, v195
	v_mov_b32_e32 v214, v200
	v_mov_b32_e32 v215, v201
	v_mov_b32_e32 v200, v196
	v_mov_b32_e32 v201, v197
	v_add_u32_e32 v185, v184, v177
	ds_read2st64_b64 v[208:211], v185 offset1:16
	v_pk_mul_f32 v[52:53], v[52:53], v[20:21]
	v_pk_mul_f32 v[56:57], v[56:57], v[186:187]
	v_pk_mul_f32 v[54:55], v[54:55], v[22:23]
	v_pk_mul_f32 v[58:59], v[58:59], v[188:189]
	v_cvt_pk_bf16_f32 v186, v52, v53
	v_cvt_pk_bf16_f32 v187, v54, v55
	v_cvt_pk_bf16_f32 v188, v56, v57
	v_cvt_pk_bf16_f32 v189, v58, v59
	v_mfma_f32_32x32x16_bf16 v[84:99], v[200:203], v[212:215], v[84:99]
	s_waitcnt lgkmcnt(0)
	v_mov_b32_e32 v22, v208
	v_mov_b32_e32 v23, v209
	v_mov_b32_e32 v208, v206
	v_mov_b32_e32 v209, v207
	v_mov_b32_e32 v20, v204
	v_mov_b32_e32 v21, v205
	v_pk_mul_f32 v[60:61], v[60:61], v[190:191]
	v_mfma_f32_32x32x16_bf16 v[68:83], v[212:215], v[186:189], v[68:83]
	ds_read_b128 v[186:189], v183 offset:33072
	v_mul_f32_e64 v62, v62, v192
	v_mul_f32_e64 v63, v63, v193
	s_waitcnt lgkmcnt(0)
	v_mul_f32_e64 v64, v64, v186
	v_mul_f32_e64 v65, v65, v187
	v_pk_mul_f32 v[66:67], v[66:67], v[188:189]
	v_cvt_pk_bf16_f32 v186, v60, v61
	v_cvt_pk_bf16_f32 v187, v62, v63
	v_cvt_pk_bf16_f32 v188, v64, v65
	v_cvt_pk_bf16_f32 v189, v66, v67
	v_mfma_f32_32x32x16_bf16 v[84:99], v[208:211], v[20:23], v[84:99]
	s_nop 0
	v_mfma_f32_32x32x16_bf16 v[68:83], v[20:23], v[186:189], v[68:83]
	v_add_u32_e32 v185, v184, v178
	ds_read_b128 v[20:23], v183 offset:33152
	ds_read_b128 v[186:189], v183 offset:33168
	ds_read_b128 v[190:193], v183 offset:33184
	ds_read_b128 v[194:197], v183 offset:33200
	ds_read2st64_b64 v[200:203], v185 offset1:16
	v_add_u32_e32 v185, v184, v179
	ds_read2st64_b64 v[204:207], v185 offset1:16
	s_waitcnt lgkmcnt(0)
	v_pk_mul_f32 v[20:21], v[156:157], v[20:21]
	v_add_u32_e32 v185, v184, v180
	v_add_u32_e32 v184, v184, v181
	ds_read2st64_b64 v[208:211], v185 offset1:16
	v_mov_b32_e32 v156, v204
	v_mov_b32_e32 v157, v205
	v_mov_b32_e32 v204, v202
	v_mov_b32_e32 v205, v203
	ds_read2st64_b64 v[212:215], v184 offset1:16
	v_pk_mul_f32 v[22:23], v[154:155], v[22:23]
	v_mov_b32_e32 v154, v200
	v_mov_b32_e32 v155, v201
	v_pk_mul_f32 v[24:25], v[24:25], v[186:187]
	s_waitcnt lgkmcnt(0)
	v_mov_b32_e32 v186, v212
	v_mfma_f32_32x32x16_bf16 v[84:99], v[204:207], v[154:157], v[84:99]
	v_mov_b32_e32 v187, v213
	v_mov_b32_e32 v212, v210
	v_mov_b32_e32 v213, v211
	v_mul_f32_e64 v28, v28, v190
	v_mul_f32_e64 v29, v29, v191
	v_pk_mul_f32 v[32:33], v[32:33], v[194:195]
	v_pk_mul_f32 v[26:27], v[26:27], v[188:189]
	v_pk_mul_f32 v[30:31], v[30:31], v[192:193]
	v_pk_mul_f32 v[34:35], v[34:35], v[196:197]
	v_mov_b32_e32 v184, v208
	v_mov_b32_e32 v185, v209
	v_cvt_pk_bf16_f32 v188, v20, v21
	v_cvt_pk_bf16_f32 v189, v22, v23
	v_cvt_pk_bf16_f32 v190, v24, v25
	v_cvt_pk_bf16_f32 v191, v26, v27
	v_cvt_pk_bf16_f32 v192, v28, v29
	v_cvt_pk_bf16_f32 v193, v30, v31
	v_cvt_pk_bf16_f32 v194, v32, v33
	v_cvt_pk_bf16_f32 v195, v34, v35
	v_mfma_f32_32x32x16_bf16 v[84:99], v[212:215], v[184:187], v[84:99]
	v_mfma_f32_32x32x16_bf16 v[68:83], v[154:157], v[188:191], v[68:83]
	v_add_u32_e32 v157, s48, v160
	s_nop 9
	v_cndmask_b32_e64 v196, 0, v84, s[8:9]
	v_cndmask_b32_e64 v197, 0, v85, s[10:11]
	v_cndmask_b32_e64 v200, 0, v86, s[12:13]
	v_cndmask_b32_e64 v201, 0, v87, s[14:15]
	v_cndmask_b32_e64 v202, 0, v88, s[16:17]
	v_cndmask_b32_e64 v203, 0, v89, s[18:19]
	v_mfma_f32_32x32x16_bf16 v[68:83], v[184:187], v[192:195], v[68:83]
	v_cndmask_b32_e64 v204, 0, v90, s[20:21]
	v_cndmask_b32_e64 v91, 0, v91, s[22:23]
	v_add3_u32 v84, v157, v161, v159
	v_add3_u32 v86, v157, v162, v159
	ds_read_b64 v[84:85], v84 offset:24576
	ds_read_b64 v[86:87], v86 offset:24576
	v_cvt_pk_bf16_f32 v88, v196, v197
	v_cvt_pk_bf16_f32 v89, v200, v201
	v_cvt_pk_bf16_f32 v90, v202, v203
	v_cvt_pk_bf16_f32 v91, v204, v91
	v_cndmask_b32_e64 v205, 0, v92, s[24:25]
	v_cndmask_b32_e64 v154, 0, v93, s[26:27]
	s_waitcnt lgkmcnt(0)
	v_mfma_f32_32x32x16_bf16 v[68:83], v[88:91], v[84:87], v[68:83]
	v_cndmask_b32_e64 v155, 0, v94, s[28:29]
	v_cndmask_b32_e64 v156, 0, v95, s[30:31]
	v_cndmask_b32_e64 v96, 0, v96, s[34:35]
	v_cndmask_b32_e64 v97, 0, v97, s[36:37]
	v_cndmask_b32_e64 v98, 0, v98, s[38:39]
	v_cndmask_b32_e64 v99, 0, v99, s[40:41]
	v_add3_u32 v92, v157, v163, v159
	v_add3_u32 v94, v157, v164, v159
	ds_read_b64 v[92:93], v92 offset:24576
	ds_read_b64 v[94:95], v94 offset:24576
	v_cvt_pk_bf16_f32 v84, v205, v154
	v_cvt_pk_bf16_f32 v85, v155, v156
	v_cvt_pk_bf16_f32 v86, v96, v97
	v_cvt_pk_bf16_f32 v87, v98, v99
	s_lshl_b32 s49, s65, 5
	s_add_i32 s49, s49, s52
	s_waitcnt lgkmcnt(0)
	v_mfma_f32_32x32x16_bf16 v[68:83], v[84:87], v[92:95], v[68:83]
	v_mad_u64_u32 v[84:85], s[66:67], s49, v199, v[120:121]
	v_lshl_add_u64 v[86:87], v[84:85], 0, v[2:3]
	s_mov_b32 s49, 0x8000
	s_nop 8
	v_cvt_pk_bf16_f32 v68, v68, s0
	global_store_short v[86:87], v68, off
	v_cvt_pk_bf16_f32 v86, v69, s0
	v_lshl_add_u64 v[68:69], v[84:85], 0, v[124:125]
	global_store_short v[68:69], v86, off
	v_add_co_u32_e32 v68, vcc, s49, v68
	v_cvt_pk_bf16_f32 v70, v70, s0
	s_nop 0
	v_addc_co_u32_e32 v69, vcc, 0, v69, vcc
	global_store_short v[68:69], v70, off offset:512
	v_cvt_pk_bf16_f32 v70, v71, s0
	v_lshl_add_u64 v[68:69], v[84:85], 0, v[126:127]
	global_store_short v[68:69], v70, off
	v_cvt_pk_bf16_f32 v70, v72, s0
	v_lshl_add_u64 v[68:69], v[84:85], 0, v[128:129]
	global_store_short v[68:69], v70, off
	v_cvt_pk_bf16_f32 v70, v73, s0
	v_lshl_add_u64 v[68:69], v[84:85], 0, v[130:131]
	global_store_short v[68:69], v70, off
	v_cvt_pk_bf16_f32 v70, v74, s0
	v_lshl_add_u64 v[68:69], v[84:85], 0, v[132:133]
	global_store_short v[68:69], v70, off
	v_cvt_pk_bf16_f32 v70, v75, s0
	v_lshl_add_u64 v[68:69], v[84:85], 0, v[134:135]
	global_store_short v[68:69], v70, off
	v_cvt_pk_bf16_f32 v70, v76, s0
	v_lshl_add_u64 v[68:69], v[84:85], 0, v[136:137]
	global_store_short v[68:69], v70, off
	v_cvt_pk_bf16_f32 v70, v77, s0
	v_lshl_add_u64 v[68:69], v[84:85], 0, v[138:139]
	global_store_short v[68:69], v70, off
	v_cvt_pk_bf16_f32 v70, v78, s0
	v_lshl_add_u64 v[68:69], v[84:85], 0, v[140:141]
	global_store_short v[68:69], v70, off
	v_cvt_pk_bf16_f32 v70, v79, s0
	v_lshl_add_u64 v[68:69], v[84:85], 0, v[142:143]
	global_store_short v[68:69], v70, off
	v_cvt_pk_bf16_f32 v70, v80, s0
	v_lshl_add_u64 v[68:69], v[84:85], 0, v[144:145]
	global_store_short v[68:69], v70, off
	v_cvt_pk_bf16_f32 v70, v81, s0
	v_lshl_add_u64 v[68:69], v[84:85], 0, v[146:147]
	global_store_short v[68:69], v70, off
	v_cvt_pk_bf16_f32 v70, v82, s0
	v_lshl_add_u64 v[68:69], v[84:85], 0, v[150:151]
	global_store_short v[68:69], v70, off
	v_cvt_pk_bf16_f32 v70, v83, s0
	v_lshl_add_u64 v[68:69], v[84:85], 0, v[152:153]
	global_store_short v[68:69], v70, off
	v_add_u32_e32 v80, s48, v182
	v_add_u32_e32 v92, v80, v165
	ds_read_b128 v[76:79], v92 offset:16384
	v_add_u32_e32 v68, v157, v165
	ds_read_b128 v[68:71], v68 offset:24576
	v_add_u32_e32 v93, v80, v166
	v_add_u32_e32 v72, v157, v166
	ds_read_b128 v[80:83], v93 offset:16384
	ds_read_b128 v[72:75], v72 offset:24576
	s_add_i32 s63, s63, -1
	s_cmp_eq_u32 s64, 8
	s_waitcnt lgkmcnt(0)
	v_mfma_f32_32x32x16_bf16 v[4:19], v[76:79], v[68:71], v[4:19]
	s_mov_b32 s66, s64
	v_mfma_f32_32x32x16_bf16 v[4:19], v[80:83], v[72:75], v[4:19]
	ds_read_b128 v[76:79], v183 offset:33280
	ds_read_b128 v[80:83], v183 offset:33296
	ds_read_b128 v[84:87], v183 offset:33312
	ds_read_b128 v[88:91], v183 offset:33328
	s_waitcnt lgkmcnt(0)
	s_nop 6
	v_pk_mul_f32 v[4:5], v[4:5], v[76:77]
	v_pk_mul_f32 v[8:9], v[8:9], v[80:81]
	v_pk_mul_f32 v[6:7], v[6:7], v[78:79]
	v_pk_mul_f32 v[10:11], v[10:11], v[82:83]
	ds_read_b128 v[76:79], v92 offset:18432
	ds_read_b128 v[80:83], v93 offset:18432
	s_waitcnt lgkmcnt(0)
	v_mfma_f32_32x32x16_bf16 v[36:51], v[76:79], v[68:71], v[36:51]
	v_mul_f32_e64 v12, v12, v84
	v_mul_f32_e64 v13, v13, v85
	v_mul_f32_e64 v16, v16, v88
	v_mul_f32_e64 v17, v17, v89
	v_mul_f32_e64 v14, v14, v86
	v_mul_f32_e64 v15, v15, v87
	v_pk_mul_f32 v[18:19], v[18:19], v[90:91]
	v_mfma_f32_32x32x16_bf16 v[36:51], v[80:83], v[72:75], v[36:51]
	ds_read_b128 v[76:79], v183 offset:33408
	ds_read_b128 v[80:83], v183 offset:33424
	ds_read_b128 v[84:87], v183 offset:33440
	ds_read_b128 v[88:91], v183 offset:33456
	s_waitcnt lgkmcnt(0)
	s_nop 6
	v_pk_mul_f32 v[36:37], v[36:37], v[76:77]
	v_pk_mul_f32 v[40:41], v[40:41], v[80:81]
	v_pk_mul_f32 v[38:39], v[38:39], v[78:79]
	v_pk_mul_f32 v[42:43], v[42:43], v[82:83]
	ds_read_b128 v[76:79], v92 offset:20480
	ds_read_b128 v[80:83], v93 offset:20480
	s_waitcnt lgkmcnt(0)
	v_mfma_f32_32x32x16_bf16 v[52:67], v[76:79], v[68:71], v[52:67]
	v_mul_f32_e64 v44, v44, v84
	v_mul_f32_e64 v45, v45, v85
	v_mul_f32_e64 v48, v48, v88
	v_mul_f32_e64 v49, v49, v89
	v_mul_f32_e64 v46, v46, v86
	v_mul_f32_e64 v47, v47, v87
	v_pk_mul_f32 v[50:51], v[50:51], v[90:91]
	v_mfma_f32_32x32x16_bf16 v[52:67], v[80:83], v[72:75], v[52:67]
	ds_read_b128 v[76:79], v183 offset:33536
	ds_read_b128 v[80:83], v183 offset:33552
	ds_read_b128 v[84:87], v183 offset:33568
	ds_read_b128 v[88:91], v183 offset:33584
	s_waitcnt lgkmcnt(0)
	s_nop 6
	v_pk_mul_f32 v[52:53], v[52:53], v[76:77]
	v_pk_mul_f32 v[56:57], v[56:57], v[80:81]
	v_pk_mul_f32 v[54:55], v[54:55], v[78:79]
	v_pk_mul_f32 v[58:59], v[58:59], v[82:83]
	ds_read_b128 v[76:79], v92 offset:22528
	ds_read_b128 v[80:83], v93 offset:22528
	s_waitcnt lgkmcnt(0)
	v_mfma_f32_32x32x16_bf16 v[20:35], v[76:79], v[68:71], v[20:35]
	v_mul_f32_e64 v60, v60, v84
	v_mul_f32_e64 v61, v61, v85
	v_mul_f32_e64 v64, v64, v88
	v_mul_f32_e64 v65, v65, v89
	v_mul_f32_e64 v62, v62, v86
	v_mul_f32_e64 v63, v63, v87
	v_pk_mul_f32 v[66:67], v[66:67], v[90:91]
	v_mfma_f32_32x32x16_bf16 v[20:35], v[80:83], v[72:75], v[20:35]
	ds_read_b128 v[68:71], v183 offset:33664
	ds_read_b128 v[72:75], v183 offset:33680
	ds_read_b128 v[76:79], v183 offset:33696
	ds_read_b128 v[80:83], v183 offset:33712
	s_cbranch_scc1 .Lhg_ctx_last
	s_waitcnt vmcnt(16) lgkmcnt(0)
	s_branch .Lhg_ctx_bar

.Lhg_ctx_bar:
	s_barrier
	s_nop 5
	v_pk_mul_f32 v[156:157], v[20:21], v[68:69]
	v_pk_mul_f32 v[24:25], v[24:25], v[72:73]
	v_pk_mul_f32 v[28:29], v[28:29], v[76:77]
	v_pk_mul_f32 v[32:33], v[32:33], v[80:81]
	v_pk_mul_f32 v[154:155], v[22:23], v[70:71]
	v_pk_mul_f32 v[26:27], v[26:27], v[74:75]
	v_pk_mul_f32 v[30:31], v[30:31], v[78:79]
	v_pk_mul_f32 v[34:35], v[34:35], v[82:83]
	s_cbranch_scc1 .LBB0_647
